# FFN-in and AB-in GEMM epilogues store write-through (sc1 dwordx4) and their grid barriers skip the L2 writeback
# baseline (speedup 1.0000x reference)
.LBB0_270:
	s_waitcnt lgkmcnt(0)
	v_mul_f32_e32 v136, 0xbfb8aa3b, v132
	v_exp_f32_e32 v136, v136
	v_mul_f32_e32 v137, 0xbfb8aa3b, v133
	v_exp_f32_e32 v137, v137
	v_mul_f32_e32 v139, 0xbfb8aa3b, v134
	v_add_f32_e32 v136, 1.0, v136
	v_rcp_f32_e32 v142, v136
	v_add_f32_e32 v136, 1.0, v137
	v_rcp_f32_e32 v143, v136
	v_exp_f32_e32 v139, v139
	s_lshl_b32 s12, s42, 8
	s_cmp_gt_i32 s72, 0
	v_pk_mul_f32 v[132:133], v[132:133], v[142:143]
	v_mul_f32_e32 v142, 0xbfb8aa3b, v135
	v_exp_f32_e32 v142, v142
	v_pk_mul_f32 v[124:125], v[132:133], v[124:125]
	v_add_f32_e32 v132, 1.0, v139
	v_mul_f32_e32 v139, 0xbfb8aa3b, v128
	v_add_f32_e32 v133, 1.0, v142
	v_rcp_f32_e32 v132, v132
	v_rcp_f32_e32 v133, v133
	v_exp_f32_e32 v139, v139
	v_mul_f32_e32 v142, 0xbfb8aa3b, v129
	v_exp_f32_e32 v142, v142
	v_pk_mul_f32 v[132:133], v[134:135], v[132:133]
	v_add_f32_e32 v134, 1.0, v139
	v_mul_f32_e32 v139, 0xbfb8aa3b, v130
	v_add_f32_e32 v135, 1.0, v142
	v_exp_f32_e32 v139, v139
	v_mul_f32_e32 v142, 0xbfb8aa3b, v131
	v_exp_f32_e32 v143, v142
	v_rcp_f32_e32 v134, v134
	v_add_f32_e32 v139, 1.0, v139
	v_rcp_f32_e32 v135, v135
	v_rcp_f32_e32 v142, v139
	v_add_f32_e32 v139, 1.0, v143
	v_rcp_f32_e32 v143, v139
	v_pk_mul_f32 v[128:129], v[128:129], v[134:135]
	v_pk_mul_f32 v[126:127], v[132:133], v[126:127]
	v_pk_mul_f32 v[128:129], v[128:129], v[120:121]
	v_pk_mul_f32 v[120:121], v[130:131], v[142:143]
	s_cselect_b32 s13, 0x80, 0
	v_pk_mul_f32 v[130:131], v[120:121], v[122:123]
	v_cvt_pk_bf16_f32 v123, v126, v127
	v_mul_f32_e32 v126, 0xbfb8aa3b, v116
	v_mul_f32_e32 v127, 0xbfb8aa3b, v117
	v_lshl_or_b32 v140, s44, 7, v7
	s_or_b32 s12, s12, s13
	v_exp_f32_e32 v126, v126
	v_exp_f32_e32 v127, v127
	v_add_u32_e32 v138, s12, v1
	v_ashrrev_i32_e32 v141, 31, v140
	v_mov_b64_e32 v[136:137], s[10:11]
	s_movk_i32 s14, 0x2c00
	v_mad_i64_i32 v[144:145], s[12:13], v138, s14, v[136:137]
	v_lshlrev_b64 v[120:121], 1, v[140:141]
	v_lshl_add_u64 v[132:133], v[144:145], 0, v[120:121]
	v_cvt_pk_bf16_f32 v122, v124, v125
	v_cvt_pk_bf16_f32 v124, v128, v129
	v_cvt_pk_bf16_f32 v125, v130, v131
	global_store_dwordx4 v[132:133], v[122:125], off sc1
	s_cmp_gt_i32 s72, -1
	s_nop 0
	v_add_f32_e32 v122, 1.0, v126
	v_add_f32_e32 v123, 1.0, v127
	v_rcp_f32_e32 v122, v122
	v_rcp_f32_e32 v123, v123
	v_or_b32_e32 v124, 16, v138
	v_mad_i64_i32 v[124:125], s[12:13], v124, s14, v[136:137]
	v_pk_mul_f32 v[116:117], v[116:117], v[122:123]
	v_mul_f32_e32 v122, 0xbfb8aa3b, v118
	v_mul_f32_e32 v123, 0xbfb8aa3b, v119
	v_exp_f32_e32 v122, v122
	v_exp_f32_e32 v123, v123
	v_pk_mul_f32 v[108:109], v[116:117], v[108:109]
	v_add_f32_e32 v116, 1.0, v122
	v_add_f32_e32 v117, 1.0, v123
	v_mul_f32_e32 v122, 0xbfb8aa3b, v112
	v_mul_f32_e32 v123, 0xbfb8aa3b, v113
	v_rcp_f32_e32 v116, v116
	v_rcp_f32_e32 v117, v117
	v_exp_f32_e32 v122, v122
	v_exp_f32_e32 v123, v123
	v_pk_mul_f32 v[116:117], v[118:119], v[116:117]
	v_add_f32_e32 v118, 1.0, v122
	v_add_f32_e32 v119, 1.0, v123
	v_mul_f32_e32 v122, 0xbfb8aa3b, v114
	v_mul_f32_e32 v123, 0xbfb8aa3b, v115
	v_exp_f32_e32 v122, v122
	v_exp_f32_e32 v123, v123
	v_rcp_f32_e32 v118, v118
	v_rcp_f32_e32 v119, v119
	v_add_f32_e32 v122, 1.0, v122
	v_add_f32_e32 v123, 1.0, v123
	v_rcp_f32_e32 v122, v122
	v_rcp_f32_e32 v123, v123
	v_pk_mul_f32 v[112:113], v[112:113], v[118:119]
	v_pk_mul_f32 v[110:111], v[116:117], v[110:111]
	v_pk_mul_f32 v[112:113], v[112:113], v[104:105]
	v_pk_mul_f32 v[104:105], v[114:115], v[122:123]
	v_lshl_add_u64 v[116:117], v[124:125], 0, v[120:121]
	v_pk_mul_f32 v[114:115], v[104:105], v[106:107]
	v_cvt_pk_bf16_f32 v104, v108, v109
	v_mul_f32_e32 v108, 0xbfb8aa3b, v100
	v_mul_f32_e32 v109, 0xbfb8aa3b, v101
	v_exp_f32_e32 v108, v108
	v_exp_f32_e32 v109, v109
	v_cvt_pk_bf16_f32 v105, v110, v111
	v_cvt_pk_bf16_f32 v106, v112, v113
	v_cvt_pk_bf16_f32 v107, v114, v115
	global_store_dwordx4 v[116:117], v[104:107], off sc1
	s_nop 1
	v_add_f32_e32 v104, 1.0, v108
	v_add_f32_e32 v105, 1.0, v109
	v_rcp_f32_e32 v104, v104
	v_rcp_f32_e32 v105, v105
	v_or_b32_e32 v106, 32, v138
	v_mad_i64_i32 v[106:107], s[12:13], v106, s14, v[136:137]
	v_pk_mul_f32 v[100:101], v[100:101], v[104:105]
	v_mul_f32_e32 v104, 0xbfb8aa3b, v102
	v_mul_f32_e32 v105, 0xbfb8aa3b, v103
	v_exp_f32_e32 v104, v104
	v_exp_f32_e32 v105, v105
	v_pk_mul_f32 v[92:93], v[100:101], v[92:93]
	v_add_f32_e32 v100, 1.0, v104
	v_add_f32_e32 v101, 1.0, v105
	v_mul_f32_e32 v104, 0xbfb8aa3b, v96
	v_mul_f32_e32 v105, 0xbfb8aa3b, v97
	v_rcp_f32_e32 v100, v100
	v_rcp_f32_e32 v101, v101
	v_exp_f32_e32 v104, v104
	v_exp_f32_e32 v105, v105
	v_pk_mul_f32 v[100:101], v[102:103], v[100:101]
	v_add_f32_e32 v102, 1.0, v104
	v_add_f32_e32 v103, 1.0, v105
	v_mul_f32_e32 v104, 0xbfb8aa3b, v98
	v_mul_f32_e32 v105, 0xbfb8aa3b, v99
	v_exp_f32_e32 v104, v104
	v_exp_f32_e32 v105, v105
	v_rcp_f32_e32 v102, v102
	v_rcp_f32_e32 v103, v103
	v_add_f32_e32 v104, 1.0, v104
	v_add_f32_e32 v105, 1.0, v105
	v_rcp_f32_e32 v104, v104
	v_rcp_f32_e32 v105, v105
	v_pk_mul_f32 v[96:97], v[96:97], v[102:103]
	v_pk_mul_f32 v[94:95], v[100:101], v[94:95]
	v_pk_mul_f32 v[96:97], v[96:97], v[88:89]
	v_pk_mul_f32 v[88:89], v[98:99], v[104:105]
	v_lshl_add_u64 v[100:101], v[106:107], 0, v[120:121]
	v_pk_mul_f32 v[98:99], v[88:89], v[90:91]
	v_cvt_pk_bf16_f32 v88, v92, v93
	v_mul_f32_e32 v92, 0xbfb8aa3b, v84
	v_mul_f32_e32 v93, 0xbfb8aa3b, v85
	v_exp_f32_e32 v92, v92
	v_exp_f32_e32 v93, v93
	v_cvt_pk_bf16_f32 v89, v94, v95
	v_cvt_pk_bf16_f32 v90, v96, v97
	v_cvt_pk_bf16_f32 v91, v98, v99
	global_store_dwordx4 v[100:101], v[88:91], off sc1
	s_nop 1
	v_add_f32_e32 v88, 1.0, v92
	v_add_f32_e32 v89, 1.0, v93
	v_rcp_f32_e32 v88, v88
	v_rcp_f32_e32 v89, v89
	v_or_b32_e32 v90, 48, v138
	v_mad_i64_i32 v[90:91], s[12:13], v90, s14, v[136:137]
	v_pk_mul_f32 v[84:85], v[84:85], v[88:89]
	v_mul_f32_e32 v88, 0xbfb8aa3b, v86
	v_mul_f32_e32 v89, 0xbfb8aa3b, v87
	v_exp_f32_e32 v88, v88
	v_exp_f32_e32 v89, v89
	v_pk_mul_f32 v[76:77], v[84:85], v[76:77]
	v_add_f32_e32 v84, 1.0, v88
	v_add_f32_e32 v85, 1.0, v89
	v_mul_f32_e32 v88, 0xbfb8aa3b, v80
	v_mul_f32_e32 v89, 0xbfb8aa3b, v81
	v_rcp_f32_e32 v84, v84
	v_rcp_f32_e32 v85, v85
	v_exp_f32_e32 v88, v88
	v_exp_f32_e32 v89, v89
	v_pk_mul_f32 v[84:85], v[86:87], v[84:85]
	v_add_f32_e32 v86, 1.0, v88
	v_add_f32_e32 v87, 1.0, v89
	v_mul_f32_e32 v88, 0xbfb8aa3b, v82
	v_mul_f32_e32 v89, 0xbfb8aa3b, v83
	v_exp_f32_e32 v88, v88
	v_exp_f32_e32 v89, v89
	v_rcp_f32_e32 v86, v86
	v_rcp_f32_e32 v87, v87
	v_add_f32_e32 v88, 1.0, v88
	v_add_f32_e32 v89, 1.0, v89
	v_rcp_f32_e32 v88, v88
	v_rcp_f32_e32 v89, v89
	v_pk_mul_f32 v[80:81], v[80:81], v[86:87]
	v_pk_mul_f32 v[78:79], v[84:85], v[78:79]
	v_pk_mul_f32 v[80:81], v[80:81], v[72:73]
	v_pk_mul_f32 v[72:73], v[82:83], v[88:89]
	v_lshl_add_u64 v[84:85], v[90:91], 0, v[120:121]
	v_pk_mul_f32 v[82:83], v[72:73], v[74:75]
	v_cvt_pk_bf16_f32 v72, v76, v77
	v_cvt_pk_bf16_f32 v73, v78, v79
	v_cvt_pk_bf16_f32 v74, v80, v81
	v_cvt_pk_bf16_f32 v75, v82, v83
	global_store_dwordx4 v[84:85], v[72:75], off sc1
	s_cbranch_scc0 .LBB0_272
	s_andn2_b64 vcc, exec, s[36:37]
	s_mov_b64 s[12:13], -1
	s_cbranch_vccnz .LBB0_244
	s_branch .LBB0_273
.LBB0_272:
	s_nop 0
	v_mul_f32_e32 v72, 0xbfb8aa3b, v68
	v_exp_f32_e32 v72, v72
	v_mul_f32_e32 v73, 0xbfb8aa3b, v69
	v_exp_f32_e32 v73, v73
	v_add_u32_e32 v76, 0x80, v138
	v_add_f32_e32 v72, 1.0, v72
	v_rcp_f32_e32 v74, v72
	v_add_f32_e32 v72, 1.0, v73
	v_rcp_f32_e32 v75, v72
	v_mov_b64_e32 v[72:73], s[10:11]
	v_mad_i64_i32 v[76:77], s[12:13], v76, s14, v[72:73]
	v_pk_mul_f32 v[68:69], v[68:69], v[74:75]
	v_mul_f32_e32 v74, 0xbfb8aa3b, v70
	v_mul_f32_e32 v75, 0xbfb8aa3b, v71
	v_exp_f32_e32 v74, v74
	v_exp_f32_e32 v75, v75
	v_pk_mul_f32 v[60:61], v[60:61], v[68:69]
	v_add_f32_e32 v68, 1.0, v74
	v_add_f32_e32 v69, 1.0, v75
	v_mul_f32_e32 v74, 0xbfb8aa3b, v64
	v_mul_f32_e32 v75, 0xbfb8aa3b, v65
	v_rcp_f32_e32 v68, v68
	v_rcp_f32_e32 v69, v69
	v_exp_f32_e32 v74, v74
	v_exp_f32_e32 v75, v75
	v_pk_mul_f32 v[68:69], v[70:71], v[68:69]
	v_add_f32_e32 v70, 1.0, v74
	v_add_f32_e32 v71, 1.0, v75
	v_mul_f32_e32 v74, 0xbfb8aa3b, v66
	v_mul_f32_e32 v75, 0xbfb8aa3b, v67
	v_exp_f32_e32 v74, v74
	v_exp_f32_e32 v75, v75
	v_rcp_f32_e32 v70, v70
	v_rcp_f32_e32 v71, v71
	v_add_f32_e32 v74, 1.0, v74
	v_add_f32_e32 v75, 1.0, v75
	v_rcp_f32_e32 v74, v74
	v_rcp_f32_e32 v75, v75
	v_pk_mul_f32 v[64:65], v[64:65], v[70:71]
	v_pk_mul_f32 v[62:63], v[62:63], v[68:69]
	v_pk_mul_f32 v[64:65], v[56:57], v[64:65]
	v_pk_mul_f32 v[56:57], v[66:67], v[74:75]
	v_lshl_add_u64 v[68:69], v[76:77], 0, v[120:121]
	v_pk_mul_f32 v[66:67], v[58:59], v[56:57]
	v_cvt_pk_bf16_f32 v56, v60, v61
	v_mul_f32_e32 v60, 0xbfb8aa3b, v52
	v_mul_f32_e32 v61, 0xbfb8aa3b, v53
	v_exp_f32_e32 v60, v60
	v_exp_f32_e32 v61, v61
	v_cvt_pk_bf16_f32 v57, v62, v63
	v_cvt_pk_bf16_f32 v58, v64, v65
	v_cvt_pk_bf16_f32 v59, v66, v67
	global_store_dwordx4 v[68:69], v[56:59], off sc1
	s_nop 1
	v_add_f32_e32 v56, 1.0, v60
	v_add_f32_e32 v57, 1.0, v61
	v_rcp_f32_e32 v56, v56
	v_rcp_f32_e32 v57, v57
	v_add_u32_e32 v58, 0x90, v138
	v_mad_i64_i32 v[58:59], s[12:13], v58, s14, v[72:73]
	v_pk_mul_f32 v[52:53], v[52:53], v[56:57]
	v_mul_f32_e32 v56, 0xbfb8aa3b, v54
	v_mul_f32_e32 v57, 0xbfb8aa3b, v55
	v_exp_f32_e32 v56, v56
	v_exp_f32_e32 v57, v57
	v_pk_mul_f32 v[44:45], v[44:45], v[52:53]
	v_add_f32_e32 v52, 1.0, v56
	v_add_f32_e32 v53, 1.0, v57
	v_mul_f32_e32 v56, 0xbfb8aa3b, v48
	v_mul_f32_e32 v57, 0xbfb8aa3b, v49
	v_rcp_f32_e32 v52, v52
	v_rcp_f32_e32 v53, v53
	v_exp_f32_e32 v56, v56
	v_exp_f32_e32 v57, v57
	v_pk_mul_f32 v[52:53], v[54:55], v[52:53]
	v_add_f32_e32 v54, 1.0, v56
	v_add_f32_e32 v55, 1.0, v57
	v_mul_f32_e32 v56, 0xbfb8aa3b, v50
	v_mul_f32_e32 v57, 0xbfb8aa3b, v51
	v_exp_f32_e32 v56, v56
	v_exp_f32_e32 v57, v57
	v_rcp_f32_e32 v54, v54
	v_rcp_f32_e32 v55, v55
	v_add_f32_e32 v56, 1.0, v56
	v_add_f32_e32 v57, 1.0, v57
	v_rcp_f32_e32 v56, v56
	v_rcp_f32_e32 v57, v57
	v_pk_mul_f32 v[48:49], v[48:49], v[54:55]
	v_pk_mul_f32 v[46:47], v[46:47], v[52:53]
	v_pk_mul_f32 v[48:49], v[40:41], v[48:49]
	v_pk_mul_f32 v[40:41], v[50:51], v[56:57]
	v_lshl_add_u64 v[52:53], v[58:59], 0, v[120:121]
	v_pk_mul_f32 v[50:51], v[42:43], v[40:41]
	v_cvt_pk_bf16_f32 v40, v44, v45
	v_mul_f32_e32 v44, 0xbfb8aa3b, v36
	v_mul_f32_e32 v45, 0xbfb8aa3b, v37
	v_exp_f32_e32 v44, v44
	v_exp_f32_e32 v45, v45
	v_cvt_pk_bf16_f32 v41, v46, v47
	v_cvt_pk_bf16_f32 v42, v48, v49
	v_cvt_pk_bf16_f32 v43, v50, v51
	global_store_dwordx4 v[52:53], v[40:43], off sc1
	s_nop 1
	v_add_f32_e32 v40, 1.0, v44
	v_add_f32_e32 v41, 1.0, v45
	v_rcp_f32_e32 v40, v40
	v_rcp_f32_e32 v41, v41
	v_add_u32_e32 v42, 0xa0, v138
	v_mad_i64_i32 v[42:43], s[12:13], v42, s14, v[72:73]
	v_pk_mul_f32 v[36:37], v[36:37], v[40:41]
	v_mul_f32_e32 v40, 0xbfb8aa3b, v38
	v_mul_f32_e32 v41, 0xbfb8aa3b, v39
	v_exp_f32_e32 v40, v40
	v_exp_f32_e32 v41, v41
	v_pk_mul_f32 v[28:29], v[28:29], v[36:37]
	v_add_f32_e32 v36, 1.0, v40
	v_add_f32_e32 v37, 1.0, v41
	v_mul_f32_e32 v40, 0xbfb8aa3b, v32
	v_mul_f32_e32 v41, 0xbfb8aa3b, v33
	v_rcp_f32_e32 v36, v36
	v_rcp_f32_e32 v37, v37
	v_exp_f32_e32 v40, v40
	v_exp_f32_e32 v41, v41
	v_pk_mul_f32 v[36:37], v[38:39], v[36:37]
	v_add_f32_e32 v38, 1.0, v40
	v_add_f32_e32 v39, 1.0, v41
	v_mul_f32_e32 v40, 0xbfb8aa3b, v34
	v_mul_f32_e32 v41, 0xbfb8aa3b, v35
	v_exp_f32_e32 v40, v40
	v_exp_f32_e32 v41, v41
	v_rcp_f32_e32 v38, v38
	v_rcp_f32_e32 v39, v39
	v_add_f32_e32 v40, 1.0, v40
	v_add_f32_e32 v41, 1.0, v41
	v_rcp_f32_e32 v40, v40
	v_rcp_f32_e32 v41, v41
	v_pk_mul_f32 v[32:33], v[32:33], v[38:39]
	v_pk_mul_f32 v[30:31], v[30:31], v[36:37]
	v_pk_mul_f32 v[32:33], v[24:25], v[32:33]
	v_pk_mul_f32 v[24:25], v[34:35], v[40:41]
	v_lshl_add_u64 v[36:37], v[42:43], 0, v[120:121]
	v_pk_mul_f32 v[34:35], v[26:27], v[24:25]
	v_cvt_pk_bf16_f32 v24, v28, v29
	v_mul_f32_e32 v28, 0xbfb8aa3b, v20
	v_mul_f32_e32 v29, 0xbfb8aa3b, v21
	v_exp_f32_e32 v28, v28
	v_exp_f32_e32 v29, v29
	v_cvt_pk_bf16_f32 v25, v30, v31
	v_cvt_pk_bf16_f32 v26, v32, v33
	v_cvt_pk_bf16_f32 v27, v34, v35
	global_store_dwordx4 v[36:37], v[24:27], off sc1
	s_nop 1
	v_add_f32_e32 v24, 1.0, v28
	v_add_f32_e32 v25, 1.0, v29
	v_rcp_f32_e32 v24, v24
	v_rcp_f32_e32 v25, v25
	v_add_u32_e32 v26, 0xb0, v138
	v_mad_i64_i32 v[26:27], s[12:13], v26, s14, v[72:73]
	v_pk_mul_f32 v[20:21], v[20:21], v[24:25]
	v_mul_f32_e32 v24, 0xbfb8aa3b, v22
	v_mul_f32_e32 v25, 0xbfb8aa3b, v23
	v_exp_f32_e32 v24, v24
	v_exp_f32_e32 v25, v25
	v_pk_mul_f32 v[12:13], v[12:13], v[20:21]
	v_add_f32_e32 v20, 1.0, v24
	v_add_f32_e32 v21, 1.0, v25
	v_mul_f32_e32 v24, 0xbfb8aa3b, v16
	v_mul_f32_e32 v25, 0xbfb8aa3b, v17
	v_rcp_f32_e32 v20, v20
	v_rcp_f32_e32 v21, v21
	v_exp_f32_e32 v24, v24
	v_exp_f32_e32 v25, v25
	v_pk_mul_f32 v[20:21], v[22:23], v[20:21]
	v_add_f32_e32 v22, 1.0, v24
	v_add_f32_e32 v23, 1.0, v25
	v_mul_f32_e32 v24, 0xbfb8aa3b, v18
	v_mul_f32_e32 v25, 0xbfb8aa3b, v19
	v_exp_f32_e32 v24, v24
	v_exp_f32_e32 v25, v25
	v_rcp_f32_e32 v22, v22
	v_rcp_f32_e32 v23, v23
	v_add_f32_e32 v24, 1.0, v24
	v_add_f32_e32 v25, 1.0, v25
	v_rcp_f32_e32 v24, v24
	v_rcp_f32_e32 v25, v25
	v_pk_mul_f32 v[16:17], v[16:17], v[22:23]
	v_pk_mul_f32 v[14:15], v[14:15], v[20:21]
	v_pk_mul_f32 v[16:17], v[8:9], v[16:17]
	v_pk_mul_f32 v[8:9], v[18:19], v[24:25]
	v_lshl_add_u64 v[20:21], v[26:27], 0, v[120:121]
	v_pk_mul_f32 v[18:19], v[10:11], v[8:9]
	v_cvt_pk_bf16_f32 v8, v12, v13
	v_cvt_pk_bf16_f32 v9, v14, v15
	v_cvt_pk_bf16_f32 v10, v16, v17
	v_cvt_pk_bf16_f32 v11, v18, v19
	global_store_dwordx4 v[20:21], v[8:11], off sc1
	s_andn2_b64 vcc, exec, s[36:37]
	s_mov_b64 s[12:13], -1
	s_cbranch_vccnz .LBB0_244

.LBB0_296:
	s_or_b64 exec, exec, s[12:13]
	v_cvt_f32_u32_e32 v7, v4
	s_waitcnt vmcnt(0)
	v_readfirstlane_b32 s12, v5
	v_sub_u32_e32 v5, 0, v4
	v_rcp_iflag_f32_e32 v7, v7
	v_add_u32_e32 v8, s12, v1
	v_mul_f32_e32 v7, 0x4f7ffffe, v7
	v_cvt_u32_f32_e32 v7, v7
	v_mul_lo_u32 v1, v5, v7
	v_mul_hi_u32 v1, v7, v1
	v_add_u32_e32 v1, v7, v1
	v_mul_hi_u32 v1, v8, v1
	v_mul_lo_u32 v5, v1, v4
	v_sub_u32_e32 v5, v8, v5
	v_add_u32_e32 v7, 1, v1
	v_cmp_ge_u32_e32 vcc, v5, v4
	s_nop 1
	v_cndmask_b32_e32 v1, v1, v7, vcc
	v_sub_u32_e32 v7, v5, v4
	v_cndmask_b32_e32 v5, v5, v7, vcc
	v_add_u32_e32 v7, 1, v1
	v_cmp_ge_u32_e32 vcc, v5, v4
	v_add_u32_e32 v5, 1, v8
	s_nop 0
	v_cndmask_b32_e32 v1, v1, v7, vcc
	v_mul_lo_u32 v7, v4, v1
	v_add_u32_e32 v4, v7, v4
	v_cmp_ne_u32_e32 vcc, v5, v4
	buffer_inv sc1
	v_add_u32_e32 v8, 1, v1
	v_readlane_b32 s14, v252, 39
	v_readlane_b32 s15, v252, 40
	s_waitcnt lgkmcnt(0)
	v_mul_lo_u32 v7, v8, v2
	v_mov_b32_e32 v5, 1
	s_mov_b32 s26, 0
	s_nop 4
	s_cbranch_vccnz .Lxb_poll_2
	s_nop 0
	s_nop 0
	global_atomic_add v3, v5, s[14:15]

.LBB0_379:
	s_lshl_b32 s6, s6, 8
	s_cmp_gt_i32 s35, 0
	s_cselect_b32 s7, 0x80, 0
	s_waitcnt lgkmcnt(0)
	v_lshl_or_b32 v136, s8, 8, v7
	s_or_b32 s6, s6, s7
	v_add_u32_e32 v138, s6, v1
	v_ashrrev_i32_e32 v137, 31, v136
	v_mov_b64_e32 v[140:141], s[16:17]
	s_movk_i32 s8, 0x1600
	v_mad_i64_i32 v[142:143], s[6:7], v138, s8, v[140:141]
	v_lshlrev_b64 v[136:137], 1, v[136:137]
	v_cvt_pk_bf16_f32 v116, v116, v117
	v_cvt_pk_bf16_f32 v117, v118, v119
	v_cvt_pk_bf16_f32 v118, v112, v113
	v_or_b32_e32 v112, 16, v138
	v_lshl_add_u64 v[142:143], v[142:143], 0, v[136:137]
	v_cvt_pk_bf16_f32 v119, v114, v115
	v_mad_i64_i32 v[112:113], s[6:7], v112, s8, v[140:141]
	v_cvt_pk_bf16_f32 v100, v100, v101
	v_cvt_pk_bf16_f32 v101, v102, v103
	v_cvt_pk_bf16_f32 v102, v96, v97
	v_or_b32_e32 v96, 32, v138
	global_store_dwordx4 v[142:143], v[116:119], off offset:256 sc1
	v_cvt_pk_bf16_f32 v103, v98, v99
	v_mad_i64_i32 v[96:97], s[6:7], v96, s8, v[140:141]
	v_lshl_add_u64 v[116:117], v[112:113], 0, v[136:137]
	v_cvt_pk_bf16_f32 v84, v84, v85
	v_cvt_pk_bf16_f32 v85, v86, v87
	v_cvt_pk_bf16_f32 v86, v80, v81
	v_or_b32_e32 v80, 48, v138
	global_store_dwordx4 v[116:117], v[100:103], off offset:256 sc1
	v_cvt_pk_bf16_f32 v87, v82, v83
	v_mad_i64_i32 v[80:81], s[6:7], v80, s8, v[140:141]
	v_lshl_add_u64 v[100:101], v[96:97], 0, v[136:137]
	s_cmp_gt_i32 s35, -1
	v_cvt_pk_bf16_f32 v132, v132, v133
	v_cvt_pk_bf16_f32 v133, v134, v135
	v_cvt_pk_bf16_f32 v134, v128, v129
	v_cvt_pk_bf16_f32 v135, v130, v131
	v_cvt_pk_bf16_f32 v112, v124, v125
	v_cvt_pk_bf16_f32 v113, v126, v127
	v_cvt_pk_bf16_f32 v114, v120, v121
	v_cvt_pk_bf16_f32 v115, v122, v123
	v_cvt_pk_bf16_f32 v96, v108, v109
	v_cvt_pk_bf16_f32 v97, v110, v111
	v_cvt_pk_bf16_f32 v98, v104, v105
	v_cvt_pk_bf16_f32 v99, v106, v107
	global_store_dwordx4 v[100:101], v[84:87], off offset:256 sc1
	v_cvt_pk_bf16_f32 v82, v88, v89
	v_cvt_pk_bf16_f32 v83, v90, v91
	v_lshl_add_u64 v[84:85], v[80:81], 0, v[136:137]
	v_cvt_pk_bf16_f32 v80, v92, v93
	v_cvt_pk_bf16_f32 v81, v94, v95
	v_cvt_pk_bf16_f32 v76, v76, v77
	v_cvt_pk_bf16_f32 v77, v78, v79
	v_cvt_pk_bf16_f32 v78, v72, v73
	v_cvt_pk_bf16_f32 v79, v74, v75
	global_store_dwordx4 v[142:143], v[132:135], off sc1
	global_store_dwordx4 v[116:117], v[112:115], off sc1
	global_store_dwordx4 v[100:101], v[96:99], off sc1
	global_store_dwordx4 v[84:85], v[80:83], off sc1
	global_store_dwordx4 v[84:85], v[76:79], off offset:256 sc1
	s_cbranch_scc0 .LBB0_381
	s_andn2_b64 vcc, exec, s[44:45]
	s_mov_b64 s[6:7], -1
	s_cbranch_vccnz .LBB0_353
	s_branch .LBB0_382
.LBB0_381:
	v_add_u32_e32 v74, 0x80, v138
	v_mov_b64_e32 v[72:73], s[16:17]
	v_cvt_pk_bf16_f32 v60, v60, v61
	v_cvt_pk_bf16_f32 v61, v62, v63
	v_cvt_pk_bf16_f32 v62, v56, v57
	v_add_u32_e32 v56, 0x90, v138
	v_cvt_pk_bf16_f32 v44, v44, v45
	v_cvt_pk_bf16_f32 v45, v46, v47
	v_cvt_pk_bf16_f32 v46, v40, v41
	v_add_u32_e32 v40, 0xa0, v138
	v_cvt_pk_bf16_f32 v28, v28, v29
	v_cvt_pk_bf16_f32 v29, v30, v31
	v_cvt_pk_bf16_f32 v30, v24, v25
	v_add_u32_e32 v24, 0xb0, v138
	v_mad_i64_i32 v[74:75], s[6:7], v74, s8, v[72:73]
	v_mad_i64_i32 v[56:57], s[6:7], v56, s8, v[72:73]
	v_mad_i64_i32 v[40:41], s[6:7], v40, s8, v[72:73]
	v_mad_i64_i32 v[24:25], s[6:7], v24, s8, v[72:73]
	v_lshl_add_u64 v[74:75], v[74:75], 0, v[136:137]
	v_cvt_pk_bf16_f32 v68, v68, v69
	v_cvt_pk_bf16_f32 v69, v70, v71
	v_cvt_pk_bf16_f32 v70, v64, v65
	v_cvt_pk_bf16_f32 v71, v66, v67
	v_cvt_pk_bf16_f32 v63, v58, v59
	v_lshl_add_u64 v[56:57], v[56:57], 0, v[136:137]
	v_cvt_pk_bf16_f32 v52, v52, v53
	v_cvt_pk_bf16_f32 v53, v54, v55
	v_cvt_pk_bf16_f32 v54, v48, v49
	v_cvt_pk_bf16_f32 v55, v50, v51
	v_cvt_pk_bf16_f32 v47, v42, v43
	v_lshl_add_u64 v[40:41], v[40:41], 0, v[136:137]
	v_cvt_pk_bf16_f32 v36, v36, v37
	v_cvt_pk_bf16_f32 v37, v38, v39
	v_cvt_pk_bf16_f32 v38, v32, v33
	v_cvt_pk_bf16_f32 v39, v34, v35
	v_cvt_pk_bf16_f32 v31, v26, v27
	v_lshl_add_u64 v[24:25], v[24:25], 0, v[136:137]
	v_cvt_pk_bf16_f32 v20, v20, v21
	v_cvt_pk_bf16_f32 v21, v22, v23
	v_cvt_pk_bf16_f32 v22, v16, v17
	v_cvt_pk_bf16_f32 v23, v18, v19
	v_cvt_pk_bf16_f32 v12, v12, v13
	v_cvt_pk_bf16_f32 v13, v14, v15
	v_cvt_pk_bf16_f32 v14, v8, v9
	v_cvt_pk_bf16_f32 v15, v10, v11
	global_store_dwordx4 v[74:75], v[68:71], off sc1
	global_store_dwordx4 v[74:75], v[60:63], off offset:256 sc1
	global_store_dwordx4 v[56:57], v[52:55], off sc1
	global_store_dwordx4 v[56:57], v[44:47], off offset:256 sc1
	global_store_dwordx4 v[40:41], v[36:39], off sc1
	global_store_dwordx4 v[40:41], v[28:31], off offset:256 sc1
	global_store_dwordx4 v[24:25], v[20:23], off sc1
	global_store_dwordx4 v[24:25], v[12:15], off offset:256 sc1
	s_andn2_b64 vcc, exec, s[44:45]
	s_mov_b64 s[6:7], -1
	s_cbranch_vccnz .LBB0_353

.LBB0_405:
	s_or_b64 exec, exec, s[10:11]
	v_cvt_f32_u32_e32 v7, v4
	s_waitcnt vmcnt(0)
	v_readfirstlane_b32 s10, v5
	v_sub_u32_e32 v5, 0, v4
	v_rcp_iflag_f32_e32 v7, v7
	v_add_u32_e32 v8, s10, v1
	v_mul_f32_e32 v7, 0x4f7ffffe, v7
	v_cvt_u32_f32_e32 v7, v7
	v_mul_lo_u32 v1, v5, v7
	v_mul_hi_u32 v1, v7, v1
	v_add_u32_e32 v1, v7, v1
	v_mul_hi_u32 v1, v8, v1
	v_mul_lo_u32 v5, v1, v4
	v_sub_u32_e32 v5, v8, v5
	v_add_u32_e32 v7, 1, v1
	v_cmp_ge_u32_e32 vcc, v5, v4
	s_nop 1
	v_cndmask_b32_e32 v1, v1, v7, vcc
	v_sub_u32_e32 v7, v5, v4
	v_cndmask_b32_e32 v5, v5, v7, vcc
	v_add_u32_e32 v7, 1, v1
	v_cmp_ge_u32_e32 vcc, v5, v4
	v_add_u32_e32 v5, 1, v8
	s_nop 0
	v_cndmask_b32_e32 v1, v1, v7, vcc
	v_mul_lo_u32 v7, v4, v1
	v_add_u32_e32 v4, v7, v4
	v_cmp_ne_u32_e32 vcc, v5, v4
	buffer_inv sc1
	v_add_u32_e32 v8, 1, v1
	v_readlane_b32 s12, v252, 39
	v_readlane_b32 s13, v252, 40
	s_waitcnt lgkmcnt(0)
	v_mul_lo_u32 v7, v8, v2
	v_mov_b32_e32 v5, 1
	s_mov_b32 s25, 0
	s_nop 4
	s_cbranch_vccnz .Lxb_poll_3
	s_nop 0
	s_nop 0
	global_atomic_add v3, v5, s[12:13]
